# speedup vs baseline: 1.0132x; 1.0039x over previous
; #define DSR(dst, addr, OFF) asm volatile("ds_read_b128 %0, %1 offset:%2" : "=&v"(dst) : "v"(addr), "i"(OFF) : "memory")
; template <int EPI>
; __device__ __forceinline__ void gemm_phase(const Params& p, const u16* __restrict__ A, const u16* __restrict__ Bt, int K, int nN,
;                            u16* __restrict__ Cout, int ldc) {
;     ...
;     for (int t = 0; t < nt; ++t) {
;       const int cur = t & 1, nb = cur ^ 1;
;       const bool last = (t + 1 == nt);
;       const bool dostage = !last || has_next;
;       const u16* pa = last ? Abn : Ab + (t + 1) * BK;
;       const u16* pb = last ? Bbn : Bb + (t + 1) * BK;
;       bf16x8 Ar[3], Bq[2][4];
;       const unsigned la_u = lds0 + (unsigned)(cur * STAGE_B + aoff), lb_u = lds0 + (unsigned)(cur * STAGE_B + boff);
;     ...
;       DSR(Bq[0][0], lb_u, 0); DSR(Bq[0][1], lb_u, 2048); DSR(Bq[0][2], lb_u, 4096); DSR(Bq[0][3], lb_u, 6144);
;       DSR(Ar[0], la_u, 0); DSR(Ar[1], la_u, 2048);
;     ...
;       GSTEP(0, 2); GSTEP(1, 6); GSTEP(2, 6); GSTEP(3, 6); GSTEP(4, 2); GSTEP(5, 2); GSTEP(6, 2); GSTEP(7, 2);
;       GSTEP(8, 2); GSTEP(9, 2); GSTEP(10, 2); GSTEP(11, 2); GSTEP(12, 2); GSTEP(13, 2); GSTEP(14, 1); GSTEP(15, 0);
.LBB0_859:
	ds_read_b128 v[0:3], v194 offset:0
	ds_read_b128 v[4:7], v194 offset:0x800
	ds_read_b128 v[8:11], v194 offset:0x1000
	ds_read_b128 v[12:15], v194 offset:0x1800
	ds_read_b128 v[16:19], v193 offset:0
	ds_read_b128 v[20:23], v193 offset:0x800
	ds_read_b128 v[24:27], v193 offset:0x1000
	s_waitcnt lgkmcnt(2)
	s_setprio 1
	v_mfma_f32_16x16x32_bf16 v[28:31], v[16:19], v[0:3], 0
	v_mfma_f32_16x16x32_bf16 v[32:35], v[16:19], v[4:7], 0
	v_mfma_f32_16x16x32_bf16 v[36:39], v[16:19], v[8:11], 0
	v_mfma_f32_16x16x32_bf16 v[16:19], v[16:19], v[12:15], 0
	s_setprio 0
	v_mov_b32_e32 v40, v176
	v_mov_b32_e32 v41, v172
	v_lshl_add_u64 v[40:41], v[40:41], 1, s[30:31]
	v_readfirstlane_b32 s17, v198
	v_lshl_add_u64 v[40:41], v[40:41], 0, s[62:63]
	s_mov_b32 m0, s17
	s_nop 0
	global_load_lds_dwordx4 v[40:41], off
	ds_read_b128 v[40:43], v193 offset:0x1800
	ds_read_b128 v[130:133], v194 offset:0x400
	ds_read_b128 v[134:137], v194 offset:0xc00
	ds_read_b128 v[138:141], v194 offset:0x1400
	ds_read_b128 v[142:145], v194 offset:0x1c00
	s_waitcnt lgkmcnt(6)
	s_setprio 1
	v_mfma_f32_16x16x32_bf16 v[44:47], v[20:23], v[0:3], 0
	v_mfma_f32_16x16x32_bf16 v[48:51], v[20:23], v[4:7], 0
	v_mfma_f32_16x16x32_bf16 v[52:55], v[20:23], v[8:11], 0
	v_mfma_f32_16x16x32_bf16 v[20:23], v[20:23], v[12:15], 0
	s_setprio 0
	v_mov_b32_e32 v56, v178
	v_mov_b32_e32 v57, v172
	v_lshl_add_u64 v[56:57], v[56:57], 1, s[30:31]
	v_readfirstlane_b32 s17, v199
	v_lshl_add_u64 v[56:57], v[56:57], 0, s[62:63]
	s_mov_b32 m0, s17
	s_nop 0
	global_load_lds_dwordx4 v[56:57], off
	ds_read_b128 v[56:59], v193 offset:0x2000
	s_waitcnt lgkmcnt(6)
	s_setprio 1
	v_mfma_f32_16x16x32_bf16 v[60:63], v[24:27], v[0:3], 0
	v_mfma_f32_16x16x32_bf16 v[64:67], v[24:27], v[4:7], 0
	v_mfma_f32_16x16x32_bf16 v[68:71], v[24:27], v[8:11], 0
	v_mfma_f32_16x16x32_bf16 v[24:27], v[24:27], v[12:15], 0
	s_setprio 0
	v_mov_b32_e32 v72, v180
	v_mov_b32_e32 v73, v172
	v_lshl_add_u64 v[72:73], v[72:73], 1, s[30:31]
	v_readfirstlane_b32 s17, v200
	v_lshl_add_u64 v[72:73], v[72:73], 0, s[62:63]
	s_mov_b32 m0, s17
	s_nop 0
	global_load_lds_dwordx4 v[72:73], off
	ds_read_b128 v[72:75], v193 offset:0x2800
	s_waitcnt lgkmcnt(6)
	s_setprio 1
	v_mfma_f32_16x16x32_bf16 v[76:79], v[40:43], v[0:3], 0
	v_mfma_f32_16x16x32_bf16 v[146:149], v[40:43], v[4:7], 0
	v_mfma_f32_16x16x32_bf16 v[150:153], v[40:43], v[8:11], 0
	v_mfma_f32_16x16x32_bf16 v[40:43], v[40:43], v[12:15], 0
	s_setprio 0
	v_mov_b32_e32 v80, v191
	v_mov_b32_e32 v81, v172
	v_lshl_add_u64 v[80:81], v[80:81], 1, s[30:31]
	v_readfirstlane_b32 s17, v201
	v_lshl_add_u64 v[80:81], v[80:81], 0, s[62:63]
	s_mov_b32 m0, s17
	s_nop 0
	global_load_lds_dwordx4 v[80:81], off
	ds_read_b128 v[80:83], v193 offset:0x3000
	s_waitcnt lgkmcnt(2)
	s_setprio 1
	v_mfma_f32_16x16x32_bf16 v[154:157], v[56:59], v[0:3], 0
	v_mfma_f32_16x16x32_bf16 v[158:161], v[56:59], v[4:7], 0
	v_mfma_f32_16x16x32_bf16 v[162:165], v[56:59], v[8:11], 0
	v_mfma_f32_16x16x32_bf16 v[166:169], v[56:59], v[12:15], 0
	s_setprio 0
	v_mov_b32_e32 v56, v176
	v_mov_b32_e32 v57, v172
	v_lshl_add_u64 v[56:57], v[56:57], 1, s[28:29]
	v_readfirstlane_b32 s17, v206
	v_lshl_add_u64 v[56:57], v[56:57], 0, s[62:63]
	s_mov_b32 m0, s17
	s_nop 0
	global_load_lds_dwordx4 v[56:57], off
	ds_read_b128 v[56:59], v193 offset:0x3800
	s_waitcnt lgkmcnt(2)
	s_setprio 1
	v_mfma_f32_16x16x32_bf16 v[208:211], v[72:75], v[0:3], 0
	v_mfma_f32_16x16x32_bf16 v[212:215], v[72:75], v[4:7], 0
	v_mfma_f32_16x16x32_bf16 v[216:219], v[72:75], v[8:11], 0
	v_mfma_f32_16x16x32_bf16 v[220:223], v[72:75], v[12:15], 0
	s_setprio 0
	v_mov_b32_e32 v72, v178
	v_mov_b32_e32 v73, v172
	v_lshl_add_u64 v[72:73], v[72:73], 1, s[28:29]
	v_readfirstlane_b32 s17, v202
	v_lshl_add_u64 v[72:73], v[72:73], 0, s[62:63]
	s_mov_b32 m0, s17
	s_nop 0
	global_load_lds_dwordx4 v[72:73], off
	ds_read_b128 v[72:75], v193 offset:0x400
	s_waitcnt lgkmcnt(2)
	s_setprio 1
	v_mfma_f32_16x16x32_bf16 v[224:227], v[80:83], v[0:3], 0
	v_mfma_f32_16x16x32_bf16 v[228:231], v[80:83], v[4:7], 0
	v_mfma_f32_16x16x32_bf16 v[232:235], v[80:83], v[8:11], 0
	v_mfma_f32_16x16x32_bf16 v[236:239], v[80:83], v[12:15], 0
	s_setprio 0
	v_mov_b32_e32 v80, v180
	v_mov_b32_e32 v81, v172
	v_lshl_add_u64 v[80:81], v[80:81], 1, s[28:29]
	v_readfirstlane_b32 s17, v203
	v_lshl_add_u64 v[80:81], v[80:81], 0, s[62:63]
	s_mov_b32 m0, s17
	s_nop 0
	global_load_lds_dwordx4 v[80:81], off
	ds_read_b128 v[80:83], v193 offset:0xc00
	s_waitcnt lgkmcnt(2)
; __device__ __forceinline__ float rsq_(float x) { return __builtin_amdgcn_rsqf(x); }
; #define WAIT_V(n) asm volatile("s_waitcnt vmcnt(%0)" ::"n"(n) : "memory")
; template <int EPI>
; __device__ __forceinline__ void gemm_phase(const Params& p, const u16* __restrict__ A, const u16* __restrict__ Bt, int K, int nN,
;                            u16* __restrict__ Cout, int ldc) {
;     ...
;       GSTEP(0, 2); GSTEP(1, 6); GSTEP(2, 6); GSTEP(3, 6); GSTEP(4, 2); GSTEP(5, 2); GSTEP(6, 2); GSTEP(7, 2);
;       GSTEP(8, 2); GSTEP(9, 2); GSTEP(10, 2); GSTEP(11, 2); GSTEP(12, 2); GSTEP(13, 2); GSTEP(14, 1); GSTEP(15, 0);
;       WAIT_V(0);
;       if (EPI != EPI_SS && t == 0 && tid < 256) rsl[tid] = rsq_(ssv * (1.f / DM) + EPS);
;       __syncthreads();
	s_setprio 1
	v_mfma_f32_16x16x32_bf16 v[0:3], v[56:59], v[0:3], 0
	v_mfma_f32_16x16x32_bf16 v[4:7], v[56:59], v[4:7], 0
	v_mfma_f32_16x16x32_bf16 v[240:243], v[56:59], v[8:11], 0
	v_mfma_f32_16x16x32_bf16 v[244:247], v[56:59], v[12:15], 0
	s_setprio 0
	v_mov_b32_e32 v8, v191
	v_mov_b32_e32 v9, v172
	v_lshl_add_u64 v[8:9], v[8:9], 1, s[28:29]
	v_readfirstlane_b32 s17, v204
	v_lshl_add_u64 v[8:9], v[8:9], 0, s[62:63]
	s_mov_b32 m0, s17
	s_nop 0
	global_load_lds_dwordx4 v[8:9], off
	ds_read_b128 v[8:11], v193 offset:0x1400
	s_waitcnt lgkmcnt(2)
	s_setprio 1
	v_mfma_f32_16x16x32_bf16 v[124:127], v[72:75], v[130:133], v[28:31]
	v_mfma_f32_16x16x32_bf16 v[120:123], v[72:75], v[134:137], v[32:35]
	v_mfma_f32_16x16x32_bf16 v[116:119], v[72:75], v[138:141], v[36:39]
	v_mfma_f32_16x16x32_bf16 v[112:115], v[72:75], v[142:145], v[16:19]
	s_setprio 0
	ds_read_b128 v[12:15], v193 offset:0x1c00
	s_waitcnt lgkmcnt(2)
	s_setprio 1
	v_mfma_f32_16x16x32_bf16 v[108:111], v[80:83], v[130:133], v[44:47]
	v_mfma_f32_16x16x32_bf16 v[104:107], v[80:83], v[134:137], v[48:51]
	v_mfma_f32_16x16x32_bf16 v[100:103], v[80:83], v[138:141], v[52:55]
	v_mfma_f32_16x16x32_bf16 v[96:99], v[80:83], v[142:145], v[20:23]
	s_setprio 0
	ds_read_b128 v[16:19], v193 offset:0x2400
	s_waitcnt lgkmcnt(2)
	s_setprio 1
	v_mfma_f32_16x16x32_bf16 v[92:95], v[8:11], v[130:133], v[60:63]
	v_mfma_f32_16x16x32_bf16 v[88:91], v[8:11], v[134:137], v[64:67]
	v_mfma_f32_16x16x32_bf16 v[84:87], v[8:11], v[138:141], v[68:71]
	v_mfma_f32_16x16x32_bf16 v[80:83], v[8:11], v[142:145], v[24:27]
	s_setprio 0
	ds_read_b128 v[8:11], v193 offset:0x2c00
	s_waitcnt lgkmcnt(2)
	s_setprio 1
	v_mfma_f32_16x16x32_bf16 v[76:79], v[12:15], v[130:133], v[76:79]
	v_mfma_f32_16x16x32_bf16 v[72:75], v[12:15], v[134:137], v[146:149]
	v_mfma_f32_16x16x32_bf16 v[68:71], v[12:15], v[138:141], v[150:153]
	v_mfma_f32_16x16x32_bf16 v[64:67], v[12:15], v[142:145], v[40:43]
	s_setprio 0
	ds_read_b128 v[12:15], v193 offset:0x3400
	s_waitcnt lgkmcnt(2)
	s_setprio 1
	v_mfma_f32_16x16x32_bf16 v[60:63], v[16:19], v[130:133], v[154:157]
	v_mfma_f32_16x16x32_bf16 v[56:59], v[16:19], v[134:137], v[158:161]
	v_mfma_f32_16x16x32_bf16 v[52:55], v[16:19], v[138:141], v[162:165]
	v_mfma_f32_16x16x32_bf16 v[48:51], v[16:19], v[142:145], v[166:169]
	s_setprio 0
	ds_read_b128 v[146:149], v193 offset:0x3c00
	s_waitcnt lgkmcnt(2)
	s_setprio 1
	v_mfma_f32_16x16x32_bf16 v[44:47], v[8:11], v[130:133], v[208:211]
	v_mfma_f32_16x16x32_bf16 v[40:43], v[8:11], v[134:137], v[212:215]
	v_mfma_f32_16x16x32_bf16 v[36:39], v[8:11], v[138:141], v[216:219]
	v_mfma_f32_16x16x32_bf16 v[32:35], v[8:11], v[142:145], v[220:223]
	s_setprio 0
	s_waitcnt lgkmcnt(1)
	s_setprio 1
	v_mfma_f32_16x16x32_bf16 v[28:31], v[12:15], v[130:133], v[224:227]
	v_mfma_f32_16x16x32_bf16 v[24:27], v[12:15], v[134:137], v[228:231]
	v_mfma_f32_16x16x32_bf16 v[20:23], v[12:15], v[138:141], v[232:235]
	v_mfma_f32_16x16x32_bf16 v[16:19], v[12:15], v[142:145], v[236:239]
	s_setprio 0
	s_waitcnt lgkmcnt(0)
	s_setprio 1
	v_mfma_f32_16x16x32_bf16 v[12:15], v[146:149], v[130:133], v[0:3]
	v_mfma_f32_16x16x32_bf16 v[8:11], v[146:149], v[134:137], v[4:7]
	v_mfma_f32_16x16x32_bf16 v[4:7], v[146:149], v[138:141], v[240:243]
	v_mfma_f32_16x16x32_bf16 v[0:3], v[146:149], v[142:145], v[244:247]
	s_setprio 0
	s_waitcnt vmcnt(0)
	s_and_saveexec_b64 s[28:29], s[0:1]
	v_fmamk_f32 v128, v128, 0x3a800000, v183
	s_nop 0
	v_rsq_f32_e32 v128, v128
	s_nop 0
	ds_write_b32 v195, v128
	s_or_b64 exec, exec, s[28:29]
	s_add_u32 s17, s42, s26
	s_addc_u32 s19, s43, s27
	s_add_u32 s30, s44, s2
	s_addc_u32 s31, s45, s3
	s_mov_b32 s34, -15
	s_waitcnt vmcnt(0) lgkmcnt(0)
	s_barrier
	v_or_b32_e32 v209, 0x10000, v194
	v_add_u32_e32 v207, 0x10000, v193
	ds_read_b128 v[212:215], v209 offset:0
	ds_read_b128 v[216:219], v209 offset:2048
	ds_read_b128 v[220:223], v209 offset:4096
	ds_read_b128 v[224:227], v209 offset:6144
	ds_read_b128 v[228:231], v207 offset:0
	ds_read_b128 v[168:171], v207 offset:2048
	ds_read_b128 v[160:163], v207 offset:4096
	v_readfirstlane_b32 s35, v175
	v_lshlrev_b32_e32 v232, 1, v176
	v_lshlrev_b32_e32 v233, 1, v178
	v_lshlrev_b32_e32 v234, 1, v180
	v_lshlrev_b32_e32 v235, 1, v191
	s_cmp_lg_u32 s34, -1
	s_cselect_b32 s28, s30, s22
	s_cselect_b32 s29, s31, s23
	s_cselect_b32 s26, s17, s24
	s_cselect_b32 s27, s19, s25
	s_cselect_b64 vcc, -1, s[20:21]

; template <int EPI>
; __device__ __forceinline__ void gemm_phase(const Params& p, const u16* __restrict__ A, const u16* __restrict__ Bt, int K, int nN,
;                            u16* __restrict__ Cout, int ldc) {
;     ...
;     if (EPI != EPI_SS && tid < 256) ssv = L_ssx[brow + tid];
.LBB0_880:
	v_add_u32_e32 v0, s16, v173
	v_ashrrev_i32_e32 v1, 31, v0
	v_lshl_add_u64 v[0:1], v[0:1], 2, s[12:13]
	global_load_dword v128, v[0:1], off
	s_or_b64 exec, exec, s[36:37]
	s_xor_b64 s[34:35], s[34:35], -1
	s_andn2_b64 vcc, exec, s[34:35]
	s_cbranch_vccz .LBB0_858
	s_branch .LBB0_859

; __device__ __forceinline__ float silu_(float x) { return x * rcp_(1.f + __expf(-x)); }
; template <int EPI>
; __device__ __forceinline__ void gemm_phase(const Params& p, const u16* __restrict__ A, const u16* __restrict__ Bt, int K, int nN,
;                            u16* __restrict__ Cout, int ldc) {
;     ...
;     if (EPI == EPI_GU) {
; #pragma unroll
;       for (int m = 0; m < 8; ++m) {
; #pragma unroll
;         for (int j = 0; j < 4; ++j) {
;           const float rs = rsl[wr * 128 + m * 16 + fqe * 4 + j];
;           u16* d = stg + (wr * 128 + m * 16 + fqe * 4 + j) * 128 + (fre & 7);
; #pragma unroll
;           for (int n2 = 0; n2 < 2; ++n2) {
;             const float g = acc[m][2 * n2][j] * rs, u = acc[m][2 * n2 + 1][j] * rs;
;             const int chunk = (wc * 4 + n2 * 2 + (fre >> 3)) ^ fqe;
;             d[chunk * 8] = f2bf(silu_(g) * u);
;           }
;         }
;         __builtin_amdgcn_sched_barrier(0);
;       }
.LBB0_1126:
	v_lshl_add_u32 v222, v192, 2, v196
	v_lshl_add_u32 v223, v222, 2, v187
	ds_read_b128 v[128:131], v223 offset:0
	ds_read_b128 v[132:135], v223 offset:64
	ds_read_b128 v[136:139], v223 offset:128
	ds_read_b128 v[140:143], v223 offset:192
	ds_read_b128 v[144:147], v223 offset:256
	ds_read_b128 v[148:151], v223 offset:320
	ds_read_b128 v[152:155], v223 offset:384
	ds_read_b128 v[156:159], v223 offset:448
	v_and_b32_e32 v224, 7, v174
	v_lshrrev_b32_e32 v225, 3, v174
	v_add_u32_e32 v225, v225, v197
	v_lshlrev_b32_e32 v224, 1, v224
	v_lshl_or_b32 v224, v222, 8, v224
	v_xor_b32_e32 v226, v225, v192
	v_add_u32_e32 v227, 2, v225
	v_xor_b32_e32 v227, v227, v192
	v_lshl_add_u32 v160, v226, 4, v224
	v_lshl_add_u32 v161, v227, 4, v224
	v_add_u32_e32 v160, 0x10000, v160
	v_add_u32_e32 v161, 0x10000, v161
	s_waitcnt lgkmcnt(0)
	v_mov_b32_e32 v228, 0xbfb8aa3b
	v_mov_b32_e32 v229, 0xbfb8aa3b
	v_mov_b32_e32 v230, 1.0
	v_mov_b32_e32 v231, 1.0
	v_pk_mul_f32 v[162:163], v[124:125], v[128:129]
	v_pk_mul_f32 v[164:165], v[126:127], v[130:131]
	v_pk_mul_f32 v[166:167], v[116:117], v[128:129]
	v_pk_mul_f32 v[168:169], v[118:119], v[130:131]
	v_pk_mul_f32 v[214:215], v[162:163], v[228:229]
	v_pk_mul_f32 v[216:217], v[164:165], v[228:229]
	v_pk_mul_f32 v[218:219], v[166:167], v[228:229]
	v_pk_mul_f32 v[220:221], v[168:169], v[228:229]
	v_exp_f32_e32 v214, v214
	v_exp_f32_e32 v215, v215
	v_exp_f32_e32 v216, v216
	v_exp_f32_e32 v217, v217
	v_exp_f32_e32 v218, v218
	v_exp_f32_e32 v219, v219
	v_exp_f32_e32 v220, v220
	v_exp_f32_e32 v221, v221
	v_pk_mul_f32 v[206:207], v[120:121], v[128:129]
	v_pk_mul_f32 v[208:209], v[122:123], v[130:131]
	v_pk_mul_f32 v[210:211], v[112:113], v[128:129]
	v_pk_mul_f32 v[212:213], v[114:115], v[130:131]
	v_pk_add_f32 v[214:215], v[214:215], v[230:231]
	v_pk_add_f32 v[216:217], v[216:217], v[230:231]
	v_pk_add_f32 v[218:219], v[218:219], v[230:231]
	v_pk_add_f32 v[220:221], v[220:221], v[230:231]
	v_rcp_f32_e32 v214, v214
	v_rcp_f32_e32 v215, v215
	v_rcp_f32_e32 v216, v216
	v_rcp_f32_e32 v217, v217
	v_rcp_f32_e32 v218, v218
	v_rcp_f32_e32 v219, v219
	v_rcp_f32_e32 v220, v220
	v_rcp_f32_e32 v221, v221
	v_pk_mul_f32 v[162:163], v[162:163], v[214:215]
	v_pk_mul_f32 v[164:165], v[164:165], v[216:217]
	v_pk_mul_f32 v[166:167], v[166:167], v[218:219]
	v_pk_mul_f32 v[168:169], v[168:169], v[220:221]
	v_pk_mul_f32 v[206:207], v[206:207], v[162:163]
	v_pk_mul_f32 v[208:209], v[208:209], v[164:165]
	v_pk_mul_f32 v[210:211], v[210:211], v[166:167]
	v_pk_mul_f32 v[212:213], v[212:213], v[168:169]
	v_cvt_pk_bf16_f32 v206, v206, v207
	v_cvt_pk_bf16_f32 v208, v208, v209
	v_cvt_pk_bf16_f32 v210, v210, v211
	v_cvt_pk_bf16_f32 v212, v212, v213
	ds_write_b16 v160, v206 offset:0
	ds_write_b16_d16_hi v160, v206 offset:256
	ds_write_b16 v160, v208 offset:512
	ds_write_b16_d16_hi v160, v208 offset:768
	ds_write_b16 v161, v210 offset:0
	ds_write_b16_d16_hi v161, v210 offset:256
	ds_write_b16 v161, v212 offset:512
	ds_write_b16_d16_hi v161, v212 offset:768
	v_pk_mul_f32 v[162:163], v[108:109], v[132:133]
	v_pk_mul_f32 v[164:165], v[110:111], v[134:135]
	v_pk_mul_f32 v[166:167], v[100:101], v[132:133]
	v_pk_mul_f32 v[168:169], v[102:103], v[134:135]
	v_pk_mul_f32 v[214:215], v[162:163], v[228:229]
	v_pk_mul_f32 v[216:217], v[164:165], v[228:229]
	v_pk_mul_f32 v[218:219], v[166:167], v[228:229]
	v_pk_mul_f32 v[220:221], v[168:169], v[228:229]
	v_exp_f32_e32 v214, v214
	v_exp_f32_e32 v215, v215
	v_exp_f32_e32 v216, v216
	v_exp_f32_e32 v217, v217
	v_exp_f32_e32 v218, v218
	v_exp_f32_e32 v219, v219
	v_exp_f32_e32 v220, v220
	v_exp_f32_e32 v221, v221
	v_pk_mul_f32 v[206:207], v[104:105], v[132:133]
	v_pk_mul_f32 v[208:209], v[106:107], v[134:135]
	v_pk_mul_f32 v[210:211], v[96:97], v[132:133]
	v_pk_mul_f32 v[212:213], v[98:99], v[134:135]
	v_pk_add_f32 v[214:215], v[214:215], v[230:231]
	v_pk_add_f32 v[216:217], v[216:217], v[230:231]
	v_pk_add_f32 v[218:219], v[218:219], v[230:231]
	v_pk_add_f32 v[220:221], v[220:221], v[230:231]
	v_rcp_f32_e32 v214, v214
	v_rcp_f32_e32 v215, v215
	v_rcp_f32_e32 v216, v216
	v_rcp_f32_e32 v217, v217
	v_rcp_f32_e32 v218, v218
	v_rcp_f32_e32 v219, v219
	v_rcp_f32_e32 v220, v220
	v_rcp_f32_e32 v221, v221
	v_pk_mul_f32 v[162:163], v[162:163], v[214:215]
	v_pk_mul_f32 v[164:165], v[164:165], v[216:217]
	v_pk_mul_f32 v[166:167], v[166:167], v[218:219]
	v_pk_mul_f32 v[168:169], v[168:169], v[220:221]
	v_pk_mul_f32 v[206:207], v[206:207], v[162:163]
	v_pk_mul_f32 v[208:209], v[208:209], v[164:165]
	v_pk_mul_f32 v[210:211], v[210:211], v[166:167]
	v_pk_mul_f32 v[212:213], v[212:213], v[168:169]
	v_cvt_pk_bf16_f32 v206, v206, v207
	v_cvt_pk_bf16_f32 v208, v208, v209
	v_cvt_pk_bf16_f32 v210, v210, v211
	v_cvt_pk_bf16_f32 v212, v212, v213
	ds_write_b16 v160, v206 offset:4096
	ds_write_b16_d16_hi v160, v206 offset:4352
	ds_write_b16 v160, v208 offset:4608
	ds_write_b16_d16_hi v160, v208 offset:4864
	ds_write_b16 v161, v210 offset:4096
	ds_write_b16_d16_hi v161, v210 offset:4352
	ds_write_b16 v161, v212 offset:4608
	ds_write_b16_d16_hi v161, v212 offset:4864
	v_pk_mul_f32 v[162:163], v[92:93], v[136:137]
	v_pk_mul_f32 v[164:165], v[94:95], v[138:139]
	v_pk_mul_f32 v[166:167], v[84:85], v[136:137]
	v_pk_mul_f32 v[168:169], v[86:87], v[138:139]
	v_pk_mul_f32 v[214:215], v[162:163], v[228:229]
	v_pk_mul_f32 v[216:217], v[164:165], v[228:229]
	v_pk_mul_f32 v[218:219], v[166:167], v[228:229]
	v_pk_mul_f32 v[220:221], v[168:169], v[228:229]
	v_exp_f32_e32 v214, v214
	v_exp_f32_e32 v215, v215
	v_exp_f32_e32 v216, v216
	v_exp_f32_e32 v217, v217
	v_exp_f32_e32 v218, v218
	v_exp_f32_e32 v219, v219
	v_exp_f32_e32 v220, v220
	v_exp_f32_e32 v221, v221
; __device__ __forceinline__ float silu_(float x) { return x * rcp_(1.f + __expf(-x)); }
; template <int EPI>
; __device__ __forceinline__ void gemm_phase(const Params& p, const u16* __restrict__ A, const u16* __restrict__ Bt, int K, int nN,
;                            u16* __restrict__ Cout, int ldc) {
;     ...
;     if (EPI == EPI_GU) {
; #pragma unroll
;       for (int m = 0; m < 8; ++m) {
; #pragma unroll
;         for (int j = 0; j < 4; ++j) {
;           const float rs = rsl[wr * 128 + m * 16 + fqe * 4 + j];
;           u16* d = stg + (wr * 128 + m * 16 + fqe * 4 + j) * 128 + (fre & 7);
; #pragma unroll
;           for (int n2 = 0; n2 < 2; ++n2) {
;             const float g = acc[m][2 * n2][j] * rs, u = acc[m][2 * n2 + 1][j] * rs;
;             const int chunk = (wc * 4 + n2 * 2 + (fre >> 3)) ^ fqe;
;             d[chunk * 8] = f2bf(silu_(g) * u);
;           }
;         }
;         __builtin_amdgcn_sched_barrier(0);
;       }
	v_pk_mul_f32 v[206:207], v[88:89], v[136:137]
	v_pk_mul_f32 v[208:209], v[90:91], v[138:139]
	v_pk_mul_f32 v[210:211], v[80:81], v[136:137]
	v_pk_mul_f32 v[212:213], v[82:83], v[138:139]
	v_pk_add_f32 v[214:215], v[214:215], v[230:231]
	v_pk_add_f32 v[216:217], v[216:217], v[230:231]
	v_pk_add_f32 v[218:219], v[218:219], v[230:231]
	v_pk_add_f32 v[220:221], v[220:221], v[230:231]
	v_rcp_f32_e32 v214, v214
	v_rcp_f32_e32 v215, v215
	v_rcp_f32_e32 v216, v216
	v_rcp_f32_e32 v217, v217
	v_rcp_f32_e32 v218, v218
	v_rcp_f32_e32 v219, v219
	v_rcp_f32_e32 v220, v220
	v_rcp_f32_e32 v221, v221
	v_pk_mul_f32 v[162:163], v[162:163], v[214:215]
	v_pk_mul_f32 v[164:165], v[164:165], v[216:217]
	v_pk_mul_f32 v[166:167], v[166:167], v[218:219]
	v_pk_mul_f32 v[168:169], v[168:169], v[220:221]
	v_pk_mul_f32 v[206:207], v[206:207], v[162:163]
	v_pk_mul_f32 v[208:209], v[208:209], v[164:165]
	v_pk_mul_f32 v[210:211], v[210:211], v[166:167]
	v_pk_mul_f32 v[212:213], v[212:213], v[168:169]
	v_cvt_pk_bf16_f32 v206, v206, v207
	v_cvt_pk_bf16_f32 v208, v208, v209
	v_cvt_pk_bf16_f32 v210, v210, v211
	v_cvt_pk_bf16_f32 v212, v212, v213
	ds_write_b16 v160, v206 offset:8192
	ds_write_b16_d16_hi v160, v206 offset:8448
	ds_write_b16 v160, v208 offset:8704
	ds_write_b16_d16_hi v160, v208 offset:8960
	ds_write_b16 v161, v210 offset:8192
	ds_write_b16_d16_hi v161, v210 offset:8448
	ds_write_b16 v161, v212 offset:8704
	ds_write_b16_d16_hi v161, v212 offset:8960
	v_pk_mul_f32 v[162:163], v[76:77], v[140:141]
	v_pk_mul_f32 v[164:165], v[78:79], v[142:143]
	v_pk_mul_f32 v[166:167], v[68:69], v[140:141]
	v_pk_mul_f32 v[168:169], v[70:71], v[142:143]
	v_pk_mul_f32 v[214:215], v[162:163], v[228:229]
	v_pk_mul_f32 v[216:217], v[164:165], v[228:229]
	v_pk_mul_f32 v[218:219], v[166:167], v[228:229]
	v_pk_mul_f32 v[220:221], v[168:169], v[228:229]
	v_exp_f32_e32 v214, v214
	v_exp_f32_e32 v215, v215
	v_exp_f32_e32 v216, v216
	v_exp_f32_e32 v217, v217
	v_exp_f32_e32 v218, v218
	v_exp_f32_e32 v219, v219
	v_exp_f32_e32 v220, v220
	v_exp_f32_e32 v221, v221
	v_pk_mul_f32 v[206:207], v[72:73], v[140:141]
	v_pk_mul_f32 v[208:209], v[74:75], v[142:143]
	v_pk_mul_f32 v[210:211], v[64:65], v[140:141]
	v_pk_mul_f32 v[212:213], v[66:67], v[142:143]
	v_pk_add_f32 v[214:215], v[214:215], v[230:231]
	v_pk_add_f32 v[216:217], v[216:217], v[230:231]
	v_pk_add_f32 v[218:219], v[218:219], v[230:231]
	v_pk_add_f32 v[220:221], v[220:221], v[230:231]
	v_rcp_f32_e32 v214, v214
	v_rcp_f32_e32 v215, v215
	v_rcp_f32_e32 v216, v216
	v_rcp_f32_e32 v217, v217
	v_rcp_f32_e32 v218, v218
	v_rcp_f32_e32 v219, v219
	v_rcp_f32_e32 v220, v220
	v_rcp_f32_e32 v221, v221
	v_pk_mul_f32 v[162:163], v[162:163], v[214:215]
	v_pk_mul_f32 v[164:165], v[164:165], v[216:217]
	v_pk_mul_f32 v[166:167], v[166:167], v[218:219]
	v_pk_mul_f32 v[168:169], v[168:169], v[220:221]
	v_pk_mul_f32 v[206:207], v[206:207], v[162:163]
	v_pk_mul_f32 v[208:209], v[208:209], v[164:165]
	v_pk_mul_f32 v[210:211], v[210:211], v[166:167]
	v_pk_mul_f32 v[212:213], v[212:213], v[168:169]
	v_cvt_pk_bf16_f32 v206, v206, v207
	v_cvt_pk_bf16_f32 v208, v208, v209
	v_cvt_pk_bf16_f32 v210, v210, v211
	v_cvt_pk_bf16_f32 v212, v212, v213
	ds_write_b16 v160, v206 offset:12288
	ds_write_b16_d16_hi v160, v206 offset:12544
	ds_write_b16 v160, v208 offset:12800
	ds_write_b16_d16_hi v160, v208 offset:13056
	ds_write_b16 v161, v210 offset:12288
	ds_write_b16_d16_hi v161, v210 offset:12544
	ds_write_b16 v161, v212 offset:12800
	ds_write_b16_d16_hi v161, v212 offset:13056
	v_pk_mul_f32 v[162:163], v[60:61], v[144:145]
	v_pk_mul_f32 v[164:165], v[62:63], v[146:147]
	v_pk_mul_f32 v[166:167], v[52:53], v[144:145]
	v_pk_mul_f32 v[168:169], v[54:55], v[146:147]
	v_pk_mul_f32 v[214:215], v[162:163], v[228:229]
	v_pk_mul_f32 v[216:217], v[164:165], v[228:229]
	v_pk_mul_f32 v[218:219], v[166:167], v[228:229]
	v_pk_mul_f32 v[220:221], v[168:169], v[228:229]
	v_exp_f32_e32 v214, v214
	v_exp_f32_e32 v215, v215
	v_exp_f32_e32 v216, v216
	v_exp_f32_e32 v217, v217
	v_exp_f32_e32 v218, v218
	v_exp_f32_e32 v219, v219
	v_exp_f32_e32 v220, v220
	v_exp_f32_e32 v221, v221
	v_pk_mul_f32 v[206:207], v[56:57], v[144:145]
	v_pk_mul_f32 v[208:209], v[58:59], v[146:147]
	v_pk_mul_f32 v[210:211], v[48:49], v[144:145]
	v_pk_mul_f32 v[212:213], v[50:51], v[146:147]
	v_pk_add_f32 v[214:215], v[214:215], v[230:231]
	v_pk_add_f32 v[216:217], v[216:217], v[230:231]
	v_pk_add_f32 v[218:219], v[218:219], v[230:231]
	v_pk_add_f32 v[220:221], v[220:221], v[230:231]
	v_rcp_f32_e32 v214, v214
	v_rcp_f32_e32 v215, v215
	v_rcp_f32_e32 v216, v216
	v_rcp_f32_e32 v217, v217
	v_rcp_f32_e32 v218, v218
	v_rcp_f32_e32 v219, v219
	v_rcp_f32_e32 v220, v220
	v_rcp_f32_e32 v221, v221
	v_pk_mul_f32 v[162:163], v[162:163], v[214:215]
	v_pk_mul_f32 v[164:165], v[164:165], v[216:217]
	v_pk_mul_f32 v[166:167], v[166:167], v[218:219]
	v_pk_mul_f32 v[168:169], v[168:169], v[220:221]
	v_pk_mul_f32 v[206:207], v[206:207], v[162:163]
	v_pk_mul_f32 v[208:209], v[208:209], v[164:165]
	v_pk_mul_f32 v[210:211], v[210:211], v[166:167]
	v_pk_mul_f32 v[212:213], v[212:213], v[168:169]
	v_cvt_pk_bf16_f32 v206, v206, v207
	v_cvt_pk_bf16_f32 v208, v208, v209
	v_cvt_pk_bf16_f32 v210, v210, v211
	v_cvt_pk_bf16_f32 v212, v212, v213
	ds_write_b16 v160, v206 offset:16384
	ds_write_b16_d16_hi v160, v206 offset:16640
	ds_write_b16 v160, v208 offset:16896
	ds_write_b16_d16_hi v160, v208 offset:17152
	ds_write_b16 v161, v210 offset:16384
	ds_write_b16_d16_hi v161, v210 offset:16640
	ds_write_b16 v161, v212 offset:16896
	ds_write_b16_d16_hi v161, v212 offset:17152
	v_pk_mul_f32 v[162:163], v[44:45], v[148:149]
	v_pk_mul_f32 v[164:165], v[46:47], v[150:151]
; __device__ __forceinline__ float silu_(float x) { return x * rcp_(1.f + __expf(-x)); }
; template <int EPI>
; __device__ __forceinline__ void gemm_phase(const Params& p, const u16* __restrict__ A, const u16* __restrict__ Bt, int K, int nN,
;                            u16* __restrict__ Cout, int ldc) {
;     ...
;     if (EPI == EPI_GU) {
; #pragma unroll
;       for (int m = 0; m < 8; ++m) {
; #pragma unroll
;         for (int j = 0; j < 4; ++j) {
;           const float rs = rsl[wr * 128 + m * 16 + fqe * 4 + j];
;           u16* d = stg + (wr * 128 + m * 16 + fqe * 4 + j) * 128 + (fre & 7);
; #pragma unroll
;           for (int n2 = 0; n2 < 2; ++n2) {
;             const float g = acc[m][2 * n2][j] * rs, u = acc[m][2 * n2 + 1][j] * rs;
;             const int chunk = (wc * 4 + n2 * 2 + (fre >> 3)) ^ fqe;
;             d[chunk * 8] = f2bf(silu_(g) * u);
;           }
;         }
;         __builtin_amdgcn_sched_barrier(0);
;       }
	v_pk_mul_f32 v[166:167], v[36:37], v[148:149]
	v_pk_mul_f32 v[168:169], v[38:39], v[150:151]
	v_pk_mul_f32 v[214:215], v[162:163], v[228:229]
	v_pk_mul_f32 v[216:217], v[164:165], v[228:229]
	v_pk_mul_f32 v[218:219], v[166:167], v[228:229]
	v_pk_mul_f32 v[220:221], v[168:169], v[228:229]
	v_exp_f32_e32 v214, v214
	v_exp_f32_e32 v215, v215
	v_exp_f32_e32 v216, v216
	v_exp_f32_e32 v217, v217
	v_exp_f32_e32 v218, v218
	v_exp_f32_e32 v219, v219
	v_exp_f32_e32 v220, v220
	v_exp_f32_e32 v221, v221
	v_pk_mul_f32 v[206:207], v[40:41], v[148:149]
	v_pk_mul_f32 v[208:209], v[42:43], v[150:151]
	v_pk_mul_f32 v[210:211], v[32:33], v[148:149]
	v_pk_mul_f32 v[212:213], v[34:35], v[150:151]
	v_pk_add_f32 v[214:215], v[214:215], v[230:231]
	v_pk_add_f32 v[216:217], v[216:217], v[230:231]
	v_pk_add_f32 v[218:219], v[218:219], v[230:231]
	v_pk_add_f32 v[220:221], v[220:221], v[230:231]
	v_rcp_f32_e32 v214, v214
	v_rcp_f32_e32 v215, v215
	v_rcp_f32_e32 v216, v216
	v_rcp_f32_e32 v217, v217
	v_rcp_f32_e32 v218, v218
	v_rcp_f32_e32 v219, v219
	v_rcp_f32_e32 v220, v220
	v_rcp_f32_e32 v221, v221
	v_pk_mul_f32 v[162:163], v[162:163], v[214:215]
	v_pk_mul_f32 v[164:165], v[164:165], v[216:217]
	v_pk_mul_f32 v[166:167], v[166:167], v[218:219]
	v_pk_mul_f32 v[168:169], v[168:169], v[220:221]
	v_pk_mul_f32 v[206:207], v[206:207], v[162:163]
	v_pk_mul_f32 v[208:209], v[208:209], v[164:165]
	v_pk_mul_f32 v[210:211], v[210:211], v[166:167]
	v_pk_mul_f32 v[212:213], v[212:213], v[168:169]
	v_cvt_pk_bf16_f32 v206, v206, v207
	v_cvt_pk_bf16_f32 v208, v208, v209
	v_cvt_pk_bf16_f32 v210, v210, v211
	v_cvt_pk_bf16_f32 v212, v212, v213
	ds_write_b16 v160, v206 offset:20480
	ds_write_b16_d16_hi v160, v206 offset:20736
	ds_write_b16 v160, v208 offset:20992
	ds_write_b16_d16_hi v160, v208 offset:21248
	ds_write_b16 v161, v210 offset:20480
	ds_write_b16_d16_hi v161, v210 offset:20736
	ds_write_b16 v161, v212 offset:20992
	ds_write_b16_d16_hi v161, v212 offset:21248
	v_pk_mul_f32 v[162:163], v[28:29], v[152:153]
	v_pk_mul_f32 v[164:165], v[30:31], v[154:155]
	v_pk_mul_f32 v[166:167], v[20:21], v[152:153]
	v_pk_mul_f32 v[168:169], v[22:23], v[154:155]
	v_pk_mul_f32 v[214:215], v[162:163], v[228:229]
	v_pk_mul_f32 v[216:217], v[164:165], v[228:229]
	v_pk_mul_f32 v[218:219], v[166:167], v[228:229]
	v_pk_mul_f32 v[220:221], v[168:169], v[228:229]
	v_exp_f32_e32 v214, v214
	v_exp_f32_e32 v215, v215
	v_exp_f32_e32 v216, v216
	v_exp_f32_e32 v217, v217
	v_exp_f32_e32 v218, v218
	v_exp_f32_e32 v219, v219
	v_exp_f32_e32 v220, v220
	v_exp_f32_e32 v221, v221
	v_pk_mul_f32 v[206:207], v[24:25], v[152:153]
	v_pk_mul_f32 v[208:209], v[26:27], v[154:155]
	v_pk_mul_f32 v[210:211], v[16:17], v[152:153]
	v_pk_mul_f32 v[212:213], v[18:19], v[154:155]
	v_pk_add_f32 v[214:215], v[214:215], v[230:231]
	v_pk_add_f32 v[216:217], v[216:217], v[230:231]
	v_pk_add_f32 v[218:219], v[218:219], v[230:231]
	v_pk_add_f32 v[220:221], v[220:221], v[230:231]
	v_rcp_f32_e32 v214, v214
	v_rcp_f32_e32 v215, v215
	v_rcp_f32_e32 v216, v216
	v_rcp_f32_e32 v217, v217
	v_rcp_f32_e32 v218, v218
	v_rcp_f32_e32 v219, v219
	v_rcp_f32_e32 v220, v220
	v_rcp_f32_e32 v221, v221
	v_pk_mul_f32 v[162:163], v[162:163], v[214:215]
	v_pk_mul_f32 v[164:165], v[164:165], v[216:217]
	v_pk_mul_f32 v[166:167], v[166:167], v[218:219]
	v_pk_mul_f32 v[168:169], v[168:169], v[220:221]
	v_pk_mul_f32 v[206:207], v[206:207], v[162:163]
	v_pk_mul_f32 v[208:209], v[208:209], v[164:165]
	v_pk_mul_f32 v[210:211], v[210:211], v[166:167]
	v_pk_mul_f32 v[212:213], v[212:213], v[168:169]
	v_cvt_pk_bf16_f32 v206, v206, v207
	v_cvt_pk_bf16_f32 v208, v208, v209
	v_cvt_pk_bf16_f32 v210, v210, v211
	v_cvt_pk_bf16_f32 v212, v212, v213
	ds_write_b16 v160, v206 offset:24576
	ds_write_b16_d16_hi v160, v206 offset:24832
	ds_write_b16 v160, v208 offset:25088
	ds_write_b16_d16_hi v160, v208 offset:25344
	ds_write_b16 v161, v210 offset:24576
	ds_write_b16_d16_hi v161, v210 offset:24832
	ds_write_b16 v161, v212 offset:25088
	ds_write_b16_d16_hi v161, v212 offset:25344
	v_pk_mul_f32 v[162:163], v[12:13], v[156:157]
	v_pk_mul_f32 v[164:165], v[14:15], v[158:159]
	v_pk_mul_f32 v[166:167], v[4:5], v[156:157]
	v_pk_mul_f32 v[168:169], v[6:7], v[158:159]
	v_pk_mul_f32 v[214:215], v[162:163], v[228:229]
	v_pk_mul_f32 v[216:217], v[164:165], v[228:229]
	v_pk_mul_f32 v[218:219], v[166:167], v[228:229]
	v_pk_mul_f32 v[220:221], v[168:169], v[228:229]
	v_exp_f32_e32 v214, v214
	v_exp_f32_e32 v215, v215
	v_exp_f32_e32 v216, v216
	v_exp_f32_e32 v217, v217
	v_exp_f32_e32 v218, v218
	v_exp_f32_e32 v219, v219
	v_exp_f32_e32 v220, v220
	v_exp_f32_e32 v221, v221
	v_pk_mul_f32 v[206:207], v[8:9], v[156:157]
	v_pk_mul_f32 v[208:209], v[10:11], v[158:159]
	v_pk_mul_f32 v[210:211], v[0:1], v[156:157]
	v_pk_mul_f32 v[212:213], v[2:3], v[158:159]
	v_pk_add_f32 v[214:215], v[214:215], v[230:231]
	v_pk_add_f32 v[216:217], v[216:217], v[230:231]
	v_pk_add_f32 v[218:219], v[218:219], v[230:231]
	v_pk_add_f32 v[220:221], v[220:221], v[230:231]
	v_rcp_f32_e32 v214, v214
	v_rcp_f32_e32 v215, v215
	v_rcp_f32_e32 v216, v216
	v_rcp_f32_e32 v217, v217
	v_rcp_f32_e32 v218, v218
	v_rcp_f32_e32 v219, v219
	v_rcp_f32_e32 v220, v220
	v_rcp_f32_e32 v221, v221
	v_pk_mul_f32 v[162:163], v[162:163], v[214:215]
	v_pk_mul_f32 v[164:165], v[164:165], v[216:217]
	v_pk_mul_f32 v[166:167], v[166:167], v[218:219]
	v_pk_mul_f32 v[168:169], v[168:169], v[220:221]
	v_pk_mul_f32 v[206:207], v[206:207], v[162:163]
	v_pk_mul_f32 v[208:209], v[208:209], v[164:165]
	v_pk_mul_f32 v[210:211], v[210:211], v[166:167]
	v_pk_mul_f32 v[212:213], v[212:213], v[168:169]
	v_cvt_pk_bf16_f32 v206, v206, v207
	v_cvt_pk_bf16_f32 v208, v208, v209
	v_cvt_pk_bf16_f32 v210, v210, v211
	v_cvt_pk_bf16_f32 v212, v212, v213
	ds_write_b16 v160, v206 offset:28672
	ds_write_b16_d16_hi v160, v206 offset:28928
	ds_write_b16 v160, v208 offset:29184
	ds_write_b16_d16_hi v160, v208 offset:29440
	ds_write_b16 v161, v210 offset:28672
	ds_write_b16_d16_hi v161, v210 offset:28928
	ds_write_b16 v161, v212 offset:29184
	ds_write_b16_d16_hi v161, v212 offset:29440
	v_mov_b32_e32 v128, v173
	v_and_b32_e32 v0, 15, v128
	v_lshrrev_b32_e32 v1, 6, v128
	v_bitop3_b32 v1, v1, v0, 3 bitop3:0x6c
	s_lshl_b32 s2, s39, 7
	v_lshl_or_b32 v8, v1, 4, v188
	v_lshl_or_b32 v0, v0, 3, s2
	v_mov_b32_e32 v1, v172
	v_ashrrev_i32_e32 v6, 4, v128
	v_lshl_add_u64 v[4:5], v[0:1], 1, s[4:5]
	v_lshl_add_u32 v0, v6, 8, v8
	s_waitcnt lgkmcnt(0)
	s_barrier
; template <int EPI>
; __device__ __forceinline__ void gemm_phase(const Params& p, const u16* __restrict__ A, const u16* __restrict__ Bt, int K, int nN,
;                            u16* __restrict__ Cout, int ldc) {
;     ...
;       __syncthreads();
; #pragma unroll
;       for (int it = 0; it < 8; ++it) {
;         const int id = it * 512 + tide, r = id >> 4, ck = id & 15;
;         const uint4 v = *(const uint4*)(stg + r * 128 + ((ck ^ ((r >> 2) & 3)) * 8));
;         { typedef __attribute__((ext_vector_type(4))) unsigned u32x4_; const u32x4_ t_ = {v.x, v.y, v.z, v.w};
;           __builtin_nontemporal_store(t_, (u32x4_*)(Cout + (unsigned)(brow + r) * (unsigned)ldc + (unsigned)((bcol >> 1) + ck * 8))); }
;       }
;       asm volatile("s_waitcnt lgkmcnt(0)" ::: "memory"); __builtin_amdgcn_s_barrier();
	ds_read_b128 v[16:19], v0 offset:0
	ds_read_b128 v[20:23], v0 offset:8192
	ds_read_b128 v[24:27], v0 offset:16384
	ds_read_b128 v[28:31], v0 offset:24576
	ds_read_b128 v[32:35], v0 offset:32768
	ds_read_b128 v[36:39], v0 offset:40960
	ds_read_b128 v[40:43], v0 offset:49152
	ds_read_b128 v[44:47], v0 offset:57344
	v_add_u32_e32 v6, s12, v6
	v_mul_lo_u32 v6, v6, s58
	v_mov_b32_e32 v7, v172
	v_lshl_add_u64 v[48:49], v[6:7], 1, v[4:5]
	s_mov_b64 s[2:3], 0x2c000
	s_mov_b64 s[26:27], -1
	s_and_b64 vcc, exec, s[14:15]
	v_lshl_add_u64 v[50:51], v[48:49], 0, s[2:3]
	v_lshl_add_u64 v[52:53], v[50:51], 0, s[2:3]
	v_lshl_add_u64 v[54:55], v[52:53], 0, s[2:3]
	v_lshl_add_u64 v[56:57], v[54:55], 0, s[2:3]
	v_lshl_add_u64 v[58:59], v[56:57], 0, s[2:3]
	v_lshl_add_u64 v[60:61], v[58:59], 0, s[2:3]
	v_lshl_add_u64 v[62:63], v[60:61], 0, s[2:3]
	s_waitcnt lgkmcnt(7)
	global_store_dwordx4 v[48:49], v[16:19], off nt
	s_waitcnt lgkmcnt(6)
	global_store_dwordx4 v[50:51], v[20:23], off nt
	s_waitcnt lgkmcnt(5)
	global_store_dwordx4 v[52:53], v[24:27], off nt
	s_waitcnt lgkmcnt(4)
	global_store_dwordx4 v[54:55], v[28:31], off nt
	s_waitcnt lgkmcnt(3)
	global_store_dwordx4 v[56:57], v[32:35], off nt
	s_waitcnt lgkmcnt(2)
	global_store_dwordx4 v[58:59], v[36:39], off nt
	s_waitcnt lgkmcnt(1)
	global_store_dwordx4 v[60:61], v[40:43], off nt
	s_waitcnt lgkmcnt(0)
	global_store_dwordx4 v[62:63], v[44:47], off nt
	s_waitcnt lgkmcnt(0)
	s_barrier
	s_cbranch_vccnz .LBB0_1153

; #define DSR(dst, addr, OFF) asm volatile("ds_read_b128 %0, %1 offset:%2" : "=&v"(dst) : "v"(addr), "i"(OFF) : "memory")
; template <int EPI>
; __device__ __forceinline__ void gemm_phase(const Params& p, const u16* __restrict__ A, const u16* __restrict__ Bt, int K, int nN,
;                            u16* __restrict__ Cout, int ldc) {
;     ...
;     for (int t = 0; t < nt; ++t) {
;       const int cur = t & 1, nb = cur ^ 1;
;       const bool last = (t + 1 == nt);
;       const bool dostage = !last || has_next;
;       const u16* pa = last ? Abn : Ab + (t + 1) * BK;
;       const u16* pb = last ? Bbn : Bb + (t + 1) * BK;
;       bf16x8 Ar[3], Bq[2][4];
;       const unsigned la_u = lds0 + (unsigned)(cur * STAGE_B + aoff), lb_u = lds0 + (unsigned)(cur * STAGE_B + boff);
;     ...
;       DSR(Bq[0][0], lb_u, 0); DSR(Bq[0][1], lb_u, 2048); DSR(Bq[0][2], lb_u, 4096); DSR(Bq[0][3], lb_u, 6144);
;       DSR(Ar[0], la_u, 0); DSR(Ar[1], la_u, 2048);
;     ...
;       GSTEP(0, 2); GSTEP(1, 6); GSTEP(2, 6); GSTEP(3, 6); GSTEP(4, 2); GSTEP(5, 2); GSTEP(6, 2); GSTEP(7, 2);
;       GSTEP(8, 2); GSTEP(9, 2); GSTEP(10, 2); GSTEP(11, 2); GSTEP(12, 2); GSTEP(13, 2); GSTEP(14, 1); GSTEP(15, 0);
.LBB0_1131:
	ds_read_b128 v[0:3], v194 offset:0
	ds_read_b128 v[4:7], v194 offset:0x800
	ds_read_b128 v[8:11], v194 offset:0x1000
	ds_read_b128 v[12:15], v194 offset:0x1800
	ds_read_b128 v[16:19], v193 offset:0
	ds_read_b128 v[20:23], v193 offset:0x800
	ds_read_b128 v[24:27], v193 offset:0x1000
	s_waitcnt lgkmcnt(2)
	s_setprio 1
	v_mfma_f32_16x16x32_bf16 v[28:31], v[16:19], v[0:3], 0
	v_mfma_f32_16x16x32_bf16 v[32:35], v[16:19], v[4:7], 0
	v_mfma_f32_16x16x32_bf16 v[36:39], v[16:19], v[8:11], 0
	v_mfma_f32_16x16x32_bf16 v[16:19], v[16:19], v[12:15], 0
	s_setprio 0
	v_mov_b32_e32 v40, v176
	v_mov_b32_e32 v41, v172
	v_lshl_add_u64 v[40:41], v[40:41], 1, s[24:25]
	v_readfirstlane_b32 s13, v198
	v_lshl_add_u64 v[40:41], v[40:41], 0, s[62:63]
	s_mov_b32 m0, s13
	s_nop 0
	global_load_lds_dwordx4 v[40:41], off
	ds_read_b128 v[40:43], v193 offset:0x1800
	ds_read_b128 v[130:133], v194 offset:0x400
	ds_read_b128 v[134:137], v194 offset:0xc00
	ds_read_b128 v[138:141], v194 offset:0x1400
	ds_read_b128 v[142:145], v194 offset:0x1c00
	s_waitcnt lgkmcnt(6)
	s_setprio 1
	v_mfma_f32_16x16x32_bf16 v[44:47], v[20:23], v[0:3], 0
	v_mfma_f32_16x16x32_bf16 v[48:51], v[20:23], v[4:7], 0
	v_mfma_f32_16x16x32_bf16 v[52:55], v[20:23], v[8:11], 0
	v_mfma_f32_16x16x32_bf16 v[20:23], v[20:23], v[12:15], 0
	s_setprio 0
	v_mov_b32_e32 v56, v178
	v_mov_b32_e32 v57, v172
	v_lshl_add_u64 v[56:57], v[56:57], 1, s[24:25]
	v_readfirstlane_b32 s13, v199
	v_lshl_add_u64 v[56:57], v[56:57], 0, s[62:63]
	s_mov_b32 m0, s13
	s_nop 0
	global_load_lds_dwordx4 v[56:57], off
	ds_read_b128 v[56:59], v193 offset:0x2000
	s_waitcnt lgkmcnt(6)
	s_setprio 1
	v_mfma_f32_16x16x32_bf16 v[60:63], v[24:27], v[0:3], 0
	v_mfma_f32_16x16x32_bf16 v[64:67], v[24:27], v[4:7], 0
	v_mfma_f32_16x16x32_bf16 v[68:71], v[24:27], v[8:11], 0
	v_mfma_f32_16x16x32_bf16 v[24:27], v[24:27], v[12:15], 0
	s_setprio 0
	v_mov_b32_e32 v72, v180
	v_mov_b32_e32 v73, v172
	v_lshl_add_u64 v[72:73], v[72:73], 1, s[24:25]
	v_readfirstlane_b32 s13, v200
	v_lshl_add_u64 v[72:73], v[72:73], 0, s[62:63]
	s_mov_b32 m0, s13
	s_nop 0
	global_load_lds_dwordx4 v[72:73], off
	ds_read_b128 v[72:75], v193 offset:0x2800
	s_waitcnt lgkmcnt(6)
	s_setprio 1
	v_mfma_f32_16x16x32_bf16 v[76:79], v[40:43], v[0:3], 0
	v_mfma_f32_16x16x32_bf16 v[146:149], v[40:43], v[4:7], 0
	v_mfma_f32_16x16x32_bf16 v[150:153], v[40:43], v[8:11], 0
	v_mfma_f32_16x16x32_bf16 v[40:43], v[40:43], v[12:15], 0
	s_setprio 0
	v_mov_b32_e32 v80, v191
	v_mov_b32_e32 v81, v172
	v_lshl_add_u64 v[80:81], v[80:81], 1, s[24:25]
	v_readfirstlane_b32 s13, v201
	v_lshl_add_u64 v[80:81], v[80:81], 0, s[62:63]
	s_mov_b32 m0, s13
	s_nop 0
	global_load_lds_dwordx4 v[80:81], off
	ds_read_b128 v[80:83], v193 offset:0x3000
	s_waitcnt lgkmcnt(2)
	s_setprio 1
	v_mfma_f32_16x16x32_bf16 v[154:157], v[56:59], v[0:3], 0
	v_mfma_f32_16x16x32_bf16 v[158:161], v[56:59], v[4:7], 0
	v_mfma_f32_16x16x32_bf16 v[162:165], v[56:59], v[8:11], 0
	v_mfma_f32_16x16x32_bf16 v[166:169], v[56:59], v[12:15], 0
	s_setprio 0
	v_mov_b32_e32 v56, v176
	v_mov_b32_e32 v57, v172
	v_lshl_add_u64 v[56:57], v[56:57], 1, s[22:23]
	v_readfirstlane_b32 s13, v205
	v_lshl_add_u64 v[56:57], v[56:57], 0, s[62:63]
	s_mov_b32 m0, s13
	s_nop 0
	global_load_lds_dwordx4 v[56:57], off
	ds_read_b128 v[56:59], v193 offset:0x3800
	s_waitcnt lgkmcnt(2)
	s_setprio 1
	v_mfma_f32_16x16x32_bf16 v[206:209], v[72:75], v[0:3], 0
	v_mfma_f32_16x16x32_bf16 v[210:213], v[72:75], v[4:7], 0
	v_mfma_f32_16x16x32_bf16 v[214:217], v[72:75], v[8:11], 0
	v_mfma_f32_16x16x32_bf16 v[218:221], v[72:75], v[12:15], 0
	s_setprio 0
	v_mov_b32_e32 v72, v178
	v_mov_b32_e32 v73, v172
	v_lshl_add_u64 v[72:73], v[72:73], 1, s[22:23]
	v_readfirstlane_b32 s13, v202
	v_lshl_add_u64 v[72:73], v[72:73], 0, s[62:63]
	s_mov_b32 m0, s13
	s_nop 0
	global_load_lds_dwordx4 v[72:73], off
	ds_read_b128 v[72:75], v193 offset:0x400
	s_waitcnt lgkmcnt(2)
	s_setprio 1
	v_mfma_f32_16x16x32_bf16 v[222:225], v[80:83], v[0:3], 0
	v_mfma_f32_16x16x32_bf16 v[226:229], v[80:83], v[4:7], 0
	v_mfma_f32_16x16x32_bf16 v[230:233], v[80:83], v[8:11], 0
	v_mfma_f32_16x16x32_bf16 v[234:237], v[80:83], v[12:15], 0
	s_setprio 0
	v_mov_b32_e32 v80, v180
	v_mov_b32_e32 v81, v172
	v_lshl_add_u64 v[80:81], v[80:81], 1, s[22:23]
	v_readfirstlane_b32 s13, v203
	v_lshl_add_u64 v[80:81], v[80:81], 0, s[62:63]
	s_mov_b32 m0, s13
	s_nop 0
	global_load_lds_dwordx4 v[80:81], off
	ds_read_b128 v[80:83], v193 offset:0xc00
	s_waitcnt lgkmcnt(2)
; __device__ __forceinline__ float rsq_(float x) { return __builtin_amdgcn_rsqf(x); }
; #define WAIT_V(n) asm volatile("s_waitcnt vmcnt(%0)" ::"n"(n) : "memory")
; template <int EPI>
; __device__ __forceinline__ void gemm_phase(const Params& p, const u16* __restrict__ A, const u16* __restrict__ Bt, int K, int nN,
;                            u16* __restrict__ Cout, int ldc) {
;     ...
;       GSTEP(0, 2); GSTEP(1, 6); GSTEP(2, 6); GSTEP(3, 6); GSTEP(4, 2); GSTEP(5, 2); GSTEP(6, 2); GSTEP(7, 2);
;       GSTEP(8, 2); GSTEP(9, 2); GSTEP(10, 2); GSTEP(11, 2); GSTEP(12, 2); GSTEP(13, 2); GSTEP(14, 1); GSTEP(15, 0);
;       WAIT_V(0);
;       if (EPI != EPI_SS && t == 0 && tid < 256) rsl[tid] = rsq_(ssv * (1.f / DM) + EPS);
;       __syncthreads();
	s_setprio 1
	v_mfma_f32_16x16x32_bf16 v[0:3], v[56:59], v[0:3], 0
	v_mfma_f32_16x16x32_bf16 v[4:7], v[56:59], v[4:7], 0
	v_mfma_f32_16x16x32_bf16 v[238:241], v[56:59], v[8:11], 0
	v_mfma_f32_16x16x32_bf16 v[242:245], v[56:59], v[12:15], 0
	s_setprio 0
	v_mov_b32_e32 v8, v191
	v_mov_b32_e32 v9, v172
	v_lshl_add_u64 v[8:9], v[8:9], 1, s[22:23]
	v_readfirstlane_b32 s13, v204
	v_lshl_add_u64 v[8:9], v[8:9], 0, s[62:63]
	s_mov_b32 m0, s13
	s_nop 0
	global_load_lds_dwordx4 v[8:9], off
	ds_read_b128 v[8:11], v193 offset:0x1400
	s_waitcnt lgkmcnt(2)
	s_setprio 1
	v_mfma_f32_16x16x32_bf16 v[124:127], v[72:75], v[130:133], v[28:31]
	v_mfma_f32_16x16x32_bf16 v[120:123], v[72:75], v[134:137], v[32:35]
	v_mfma_f32_16x16x32_bf16 v[116:119], v[72:75], v[138:141], v[36:39]
	v_mfma_f32_16x16x32_bf16 v[112:115], v[72:75], v[142:145], v[16:19]
	s_setprio 0
	ds_read_b128 v[12:15], v193 offset:0x1c00
	s_waitcnt lgkmcnt(2)
	s_setprio 1
	v_mfma_f32_16x16x32_bf16 v[108:111], v[80:83], v[130:133], v[44:47]
	v_mfma_f32_16x16x32_bf16 v[104:107], v[80:83], v[134:137], v[48:51]
	v_mfma_f32_16x16x32_bf16 v[100:103], v[80:83], v[138:141], v[52:55]
	v_mfma_f32_16x16x32_bf16 v[96:99], v[80:83], v[142:145], v[20:23]
	s_setprio 0
	ds_read_b128 v[16:19], v193 offset:0x2400
	s_waitcnt lgkmcnt(2)
	s_setprio 1
	v_mfma_f32_16x16x32_bf16 v[92:95], v[8:11], v[130:133], v[60:63]
	v_mfma_f32_16x16x32_bf16 v[88:91], v[8:11], v[134:137], v[64:67]
	v_mfma_f32_16x16x32_bf16 v[84:87], v[8:11], v[138:141], v[68:71]
	v_mfma_f32_16x16x32_bf16 v[80:83], v[8:11], v[142:145], v[24:27]
	s_setprio 0
	ds_read_b128 v[8:11], v193 offset:0x2c00
	s_waitcnt lgkmcnt(2)
	s_setprio 1
	v_mfma_f32_16x16x32_bf16 v[76:79], v[12:15], v[130:133], v[76:79]
	v_mfma_f32_16x16x32_bf16 v[72:75], v[12:15], v[134:137], v[146:149]
	v_mfma_f32_16x16x32_bf16 v[68:71], v[12:15], v[138:141], v[150:153]
	v_mfma_f32_16x16x32_bf16 v[64:67], v[12:15], v[142:145], v[40:43]
	s_setprio 0
	ds_read_b128 v[12:15], v193 offset:0x3400
	s_waitcnt lgkmcnt(2)
	s_setprio 1
	v_mfma_f32_16x16x32_bf16 v[60:63], v[16:19], v[130:133], v[154:157]
	v_mfma_f32_16x16x32_bf16 v[56:59], v[16:19], v[134:137], v[158:161]
	v_mfma_f32_16x16x32_bf16 v[52:55], v[16:19], v[138:141], v[162:165]
	v_mfma_f32_16x16x32_bf16 v[48:51], v[16:19], v[142:145], v[166:169]
	s_setprio 0
	ds_read_b128 v[146:149], v193 offset:0x3c00
	s_waitcnt lgkmcnt(2)
	s_setprio 1
	v_mfma_f32_16x16x32_bf16 v[44:47], v[8:11], v[130:133], v[206:209]
	v_mfma_f32_16x16x32_bf16 v[40:43], v[8:11], v[134:137], v[210:213]
	v_mfma_f32_16x16x32_bf16 v[36:39], v[8:11], v[138:141], v[214:217]
	v_mfma_f32_16x16x32_bf16 v[32:35], v[8:11], v[142:145], v[218:221]
	s_setprio 0
	s_waitcnt lgkmcnt(1)
	s_setprio 1
	v_mfma_f32_16x16x32_bf16 v[28:31], v[12:15], v[130:133], v[222:225]
	v_mfma_f32_16x16x32_bf16 v[24:27], v[12:15], v[134:137], v[226:229]
	v_mfma_f32_16x16x32_bf16 v[20:23], v[12:15], v[138:141], v[230:233]
	v_mfma_f32_16x16x32_bf16 v[16:19], v[12:15], v[142:145], v[234:237]
	s_setprio 0
	s_waitcnt lgkmcnt(0)
	s_setprio 1
	v_mfma_f32_16x16x32_bf16 v[12:15], v[146:149], v[130:133], v[0:3]
	v_mfma_f32_16x16x32_bf16 v[8:11], v[146:149], v[134:137], v[4:7]
	v_mfma_f32_16x16x32_bf16 v[4:7], v[146:149], v[138:141], v[238:241]
	v_mfma_f32_16x16x32_bf16 v[0:3], v[146:149], v[142:145], v[242:245]
	s_setprio 0
	s_waitcnt vmcnt(0)
	s_and_saveexec_b64 s[22:23], s[0:1]
	v_fmamk_f32 v128, v128, 0x3a800000, v183
	s_nop 0
	v_rsq_f32_e32 v128, v128
	s_nop 0
	ds_write_b32 v195, v128
	s_or_b64 exec, exec, s[22:23]
	s_add_u32 s13, s35, s20
	s_addc_u32 s24, s36, s21
	s_add_u32 s25, s37, s2
	s_addc_u32 s26, s38, s3
	s_mov_b32 s27, -15
	s_waitcnt vmcnt(0) lgkmcnt(0)
	s_barrier
	v_or_b32_e32 v208, 0x10000, v194
	v_add_u32_e32 v206, 0x10000, v193
	ds_read_b128 v[212:215], v208 offset:0
	ds_read_b128 v[216:219], v208 offset:2048
	ds_read_b128 v[220:223], v208 offset:4096
	ds_read_b128 v[224:227], v208 offset:6144
	ds_read_b128 v[228:231], v206 offset:0
	ds_read_b128 v[168:171], v206 offset:2048
	ds_read_b128 v[160:163], v206 offset:4096
	v_readfirstlane_b32 s40, v175
	v_lshlrev_b32_e32 v232, 1, v176
	v_lshlrev_b32_e32 v233, 1, v178
	v_lshlrev_b32_e32 v234, 1, v180
	v_lshlrev_b32_e32 v235, 1, v191
	s_cmp_lg_u32 s27, -1
	s_cselect_b32 s22, s25, s16
	s_cselect_b32 s23, s26, s17
	s_cselect_b32 s20, s13, s18
	s_cselect_b32 s21, s24, s19
	s_cselect_b64 vcc, -1, s[10:11]

; template <int EPI>
; __device__ __forceinline__ void gemm_phase(const Params& p, const u16* __restrict__ A, const u16* __restrict__ Bt, int K, int nN,
;                            u16* __restrict__ Cout, int ldc) {
;     ...
;     if (EPI != EPI_SS && tid < 256) ssv = L_ssx[brow + tid];
.LBB0_1152:
	v_add_u32_e32 v0, s12, v173
	v_ashrrev_i32_e32 v1, 31, v0
	v_lshl_add_u64 v[0:1], v[0:1], 2, s[6:7]
	global_load_dword v128, v[0:1], off
	s_or_b64 exec, exec, s[28:29]
	s_xor_b64 s[26:27], s[26:27], -1
	s_andn2_b64 vcc, exec, s[26:27]
	s_cbranch_vccz .LBB0_1130
	s_branch .LBB0_1131
